# sc1 write-through scope on the mixer BR stores (diff / FoX / gMLP / mem attention outputs), on top of v11
# speedup vs baseline: 1.0012x; 1.0009x over previous
; #define LAS __attribute__((address_space(3)))
; template <int MODE>
; __device__ __forceinline__ void attn_item(LAS unsigned char* lds, const AttnArgs& a, const int tid) {
;     ...
; #pragma unroll 4
;         for (int i = 0; i < 8; ++i) { const u32x4 ov = *(const LAS u32x4*)(lds + off_b(r0 + 32 * i, ch)); *(u32x4*)(a.O + (size_t)(a.q0 + r0 + 32 * i) * a.ldo + 8 * ch) = ov; }
.LBB0_72:
	ds_read_b128 v[8:11], v0
	v_add_u32_e32 v4, s18, v6
	v_ashrrev_i32_e32 v5, 31, v4
	v_lshlrev_b64 v[12:13], 12, v[4:5]
	v_lshl_add_u64 v[12:13], v[2:3], 0, v[12:13]
	s_waitcnt lgkmcnt(0)
	global_store_dwordx4 v[12:13], v[8:11], off sc1
	ds_read_b128 v[8:11], v0 offset:8192
	v_add_u32_e32 v12, 32, v4
	v_ashrrev_i32_e32 v13, 31, v12
	v_lshlrev_b64 v[12:13], 12, v[12:13]
	v_lshl_add_u64 v[12:13], v[2:3], 0, v[12:13]
	s_waitcnt lgkmcnt(0)
	global_store_dwordx4 v[12:13], v[8:11], off sc1
	ds_read_b128 v[8:11], v0 offset:16384
	v_add_u32_e32 v12, 64, v4
	v_ashrrev_i32_e32 v13, 31, v12
	v_lshlrev_b64 v[12:13], 12, v[12:13]
	v_lshl_add_u64 v[12:13], v[2:3], 0, v[12:13]
	s_waitcnt lgkmcnt(0)
	global_store_dwordx4 v[12:13], v[8:11], off sc1
	ds_read_b128 v[8:11], v0 offset:24576
	v_add_u32_e32 v4, 0x60, v4
	v_ashrrev_i32_e32 v5, 31, v4
	v_lshlrev_b64 v[4:5], 12, v[4:5]
	s_addk_i32 s18, 0x80
	v_lshl_add_u64 v[4:5], v[2:3], 0, v[4:5]
	v_add_u32_e32 v0, 0x8000, v0
	s_cmpk_lg_i32 s18, 0x100
	s_waitcnt lgkmcnt(0)
	global_store_dwordx4 v[4:5], v[8:11], off sc1
	s_cbranch_scc1 .LBB0_72
	v_readlane_b32 s18, v252, 42
	s_add_i32 s46, s46, s64
	s_add_i32 s45, s45, s18
	s_cmpk_gt_i32 s46, 0x5ff
	s_cbranch_scc0 .LBB0_50
	s_movk_i32 s59, 0x200
	s_movk_i32 s62, 0x5800
	s_mov_b32 s28, 0x3a2aaaab
	s_movk_i32 s63, 0x100

; #define LAS __attribute__((address_space(3)))
; __device__ __forceinline__ float bflo(unsigned w) { return __uint_as_float(w << 16); }
; __device__ __forceinline__ float bfhi(unsigned w) { return __uint_as_float(w & 0xffff0000u); }
; __device__ __forceinline__ unsigned pk2(float lo, float hi) { const f32x2v v = {lo, hi}; return __builtin_bit_cast(unsigned, __builtin_convertvector(v, bf16x2v)); }
; __device__ __forceinline__ void gmlp_item(LAS unsigned char* lds, const bf16_t* Zt  , bf16_t* BRt  , const bf16_t* wsb, const float* bs_, const float* lng, const float* lnb, const int tid) {
;     ...
;     for (int g = 0; g < 12; ++g) {
;         GM_LOAD(g);
;         { const int ch = tid & 15, t0 = tid >> 4;
;           if (g > 0) {
; #pragma unroll
;               for (int i = 0; i < 4; ++i) { const int t = t0 + 32 * i; const u32x4 ov = *(const LAS u32x4*)(lds + 65536 + off_b(t, ch)); *(u32x4*)(BRt + (size_t)t * DM + (g - 1) * 128 + 8 * ch) = ov; } }
;           const float* gp = lng + g * 128 + 8 * ch; const float* bp = lnb + g * 128 + 8 * ch;
;           const f32x4 g0 = *(const f32x4*)gp, g1 = *(const f32x4*)(gp + 4), b0 = *(const f32x4*)bp, b1 = *(const f32x4*)(bp + 4);
; #pragma unroll
;           for (int i = 0; i < 4; ++i) { const int t = t0 + 32 * i;
;               *(LAS u32x4*)(lds + off_b(t, ch)) = wb[i];
;               const float mean = st[2 * t], rstd = st[2 * t + 1];
;               u32x4 o;
;               o.x = pk2((bflo(vw[i].x) - mean) * rstd * g0[0] + b0[0], (bfhi(vw[i].x) - mean) * rstd * g0[1] + b0[1]);
;               o.y = pk2((bflo(vw[i].y) - mean) * rstd * g0[2] + b0[2], (bfhi(vw[i].y) - mean) * rstd * g0[3] + b0[3]);
;               o.z = pk2((bflo(vw[i].z) - mean) * rstd * g1[0] + b1[0], (bfhi(vw[i].z) - mean) * rstd * g1[1] + b1[1]);
;               o.w = pk2((bflo(vw[i].w) - mean) * rstd * g1[2] + b1[2], (bfhi(vw[i].w) - mean) * rstd * g1[3] + b1[3]);
;               *(LAS u32x4*)(lds + 32768 + off_b(t, ch)) = o;
;               *(LAS u32x4*)(lds + 65536 + off_b(t, ch)) = uu[i]; *(LAS u32x4*)(lds + 98304 + off_b(t, ch)) = gg4[i]; } }
.LBB0_90:
	v_lshl_add_u64 v[2:3], v[122:123], 0, v[76:77]
	v_lshl_add_u64 v[54:55], v[124:125], 0, v[76:77]
	global_load_dwordx4 v[14:17], v[2:3], off
	v_add_co_u32_e32 v2, vcc, 0x1b100000, v54
	v_lshl_add_u64 v[18:19], v[66:67], 0, v[76:77]
	s_nop 0
	v_addc_co_u32_e32 v3, vcc, 0, v55, vcc
	v_add_co_u32_e32 v6, vcc, 0x1b101000, v54
	global_load_dwordx4 v[10:13], v[2:3], off offset:3328
	s_nop 0
	global_load_dwordx4 v[2:5], v[2:3], off offset:256
	v_addc_co_u32_e32 v7, vcc, 0, v55, vcc
	global_load_dwordx4 v[30:33], v[18:19], off
	v_add_co_u32_e32 v18, vcc, 0x1b158000, v54
	v_lshl_add_u64 v[34:35], v[68:69], 0, v[76:77]
	s_nop 0
	v_addc_co_u32_e32 v19, vcc, 0, v55, vcc
	v_add_co_u32_e32 v22, vcc, 0x1b159000, v54
	global_load_dwordx4 v[6:9], v[6:7], off offset:3328
	s_nop 0
	v_addc_co_u32_e32 v23, vcc, 0, v55, vcc
	global_load_dwordx4 v[26:29], v[18:19], off offset:3328
	s_nop 0
	global_load_dwordx4 v[18:21], v[18:19], off offset:256
	v_lshl_add_u64 v[50:51], v[70:71], 0, v[76:77]
	global_load_dwordx4 v[46:49], v[34:35], off
	v_add_co_u32_e32 v34, vcc, 0x1b1b0000, v54
	global_load_dwordx4 v[22:25], v[22:23], off offset:3328
	s_nop 0
	v_addc_co_u32_e32 v35, vcc, 0, v55, vcc
	v_add_co_u32_e32 v38, vcc, 0x1b1b1000, v54
	global_load_dwordx4 v[42:45], v[34:35], off offset:3328
	s_nop 0
	global_load_dwordx4 v[34:37], v[34:35], off offset:256
	v_addc_co_u32_e32 v39, vcc, 0, v55, vcc
	global_load_dwordx4 v[62:65], v[50:51], off
	v_add_co_u32_e32 v50, vcc, 0x1b208000, v54
	v_add_u32_e32 v196, v137, v138
	s_nop 0
	v_addc_co_u32_e32 v51, vcc, 0, v55, vcc
	global_load_dwordx4 v[38:41], v[38:39], off offset:3328
	s_nop 0
	global_load_dwordx4 v[58:61], v[50:51], off offset:3328
	s_nop 0
	global_load_dwordx4 v[50:53], v[50:51], off offset:256
	ds_read_b128 v[198:201], v196
	v_add_co_u32_e32 v54, vcc, 0x1b209000, v54
	v_lshl_add_u64 v[218:219], v[72:73], 0, v[76:77]
	s_nop 0
	v_addc_co_u32_e32 v55, vcc, 0, v55, vcc
	v_add_co_u32_e32 v214, vcc, 0x13100000, v218
	global_load_dwordx4 v[54:57], v[54:55], off offset:3328
	s_nop 0
	v_addc_co_u32_e32 v215, vcc, 0, v219, vcc
	s_waitcnt lgkmcnt(0)
	global_store_dwordx4 v[214:215], v[198:201], off sc1
	v_add_u32_e32 v197, v137, v139
	ds_read_b128 v[198:201], v197
	v_add_co_u32_e32 v214, vcc, 0x13120000, v218
	v_lshl_add_u64 v[226:227], v[80:81], 0, s[10:11]
	s_nop 0
	v_addc_co_u32_e32 v215, vcc, 0, v219, vcc
	s_waitcnt lgkmcnt(0)
	global_store_dwordx4 v[214:215], v[198:201], off sc1
	v_lshl_add_u64 v[124:125], v[124:125], 0, s[56:57]
	v_lshl_add_u64 v[122:123], v[122:123], 0, s[0:1]
	v_add_u32_e32 v198, v137, v140
	ds_read_b128 v[214:217], v198
	v_add_co_u32_e32 v200, vcc, 0x13140000, v218
	v_add_u32_e32 v199, v137, v141
	s_nop 0
	v_addc_co_u32_e32 v201, vcc, 0, v219, vcc
	s_waitcnt lgkmcnt(0)
	global_store_dwordx4 v[200:201], v[214:217], off sc1
	ds_read_b128 v[214:217], v199
	v_add_co_u32_e32 v200, vcc, 0x13160000, v218
	v_lshl_add_u64 v[72:73], v[72:73], 0, s[56:57]
	s_nop 0
	v_addc_co_u32_e32 v201, vcc, 0, v219, vcc
	s_waitcnt lgkmcnt(0)
	global_store_dwordx4 v[200:201], v[214:217], off sc1
	v_lshl_add_u64 v[200:201], v[78:79], 0, s[10:11]
	global_load_dwordx4 v[214:217], v[200:201], off offset:528
	global_load_dwordx4 v[218:221], v[200:201], off offset:512
	global_load_dwordx4 v[222:225], v[226:227], off offset:528
	global_load_dwordx4 v[232:235], v[226:227], off offset:512
	s_waitcnt vmcnt(0)
	ds_write_b128 v160, v[14:17]
	ds_read_b64 v[14:15], v161
	s_add_u32 s10, s10, 0x200
	s_addc_u32 s11, s11, 0
	v_lshl_add_u64 v[70:71], v[70:71], 0, s[0:1]
	v_lshlrev_b32_e32 v16, 16, v10
	v_and_b32_e32 v17, 0xffff0000, v10
	s_waitcnt lgkmcnt(0)
	v_pk_add_f32 v[16:17], v[16:17], v[14:15] op_sel_hi:[1,0] neg_lo:[0,1] neg_hi:[0,1]
	v_lshl_add_u64 v[68:69], v[68:69], 0, s[0:1]
	v_pk_mul_f32 v[16:17], v[14:15], v[16:17] op_sel:[1,0]
	v_lshl_add_u64 v[66:67], v[66:67], 0, s[0:1]
	v_pk_fma_f32 v[16:17], v[218:219], v[16:17], v[232:233]
	s_nop 0
	v_cvt_pk_bf16_f32 v10, v16, v17
	v_lshlrev_b32_e32 v16, 16, v11
	v_and_b32_e32 v17, 0xffff0000, v11
	v_pk_add_f32 v[16:17], v[16:17], v[14:15] op_sel_hi:[1,0] neg_lo:[0,1] neg_hi:[0,1]
	s_nop 0
	v_pk_mul_f32 v[16:17], v[14:15], v[16:17] op_sel:[1,0]
	s_nop 0
	v_pk_fma_f32 v[16:17], v[220:221], v[16:17], v[234:235]
	s_nop 0
	v_cvt_pk_bf16_f32 v11, v16, v17
	v_lshlrev_b32_e32 v16, 16, v12
	v_and_b32_e32 v17, 0xffff0000, v12
	v_pk_add_f32 v[16:17], v[16:17], v[14:15] op_sel_hi:[1,0] neg_lo:[0,1] neg_hi:[0,1]
	s_nop 0
	v_pk_mul_f32 v[16:17], v[14:15], v[16:17] op_sel:[1,0]
	s_nop 0
	v_pk_fma_f32 v[16:17], v[214:215], v[16:17], v[222:223]
	s_nop 0
	v_cvt_pk_bf16_f32 v12, v16, v17
	v_lshlrev_b32_e32 v16, 16, v13
	v_and_b32_e32 v17, 0xffff0000, v13
	v_pk_add_f32 v[16:17], v[16:17], v[14:15] op_sel_hi:[1,0] neg_lo:[0,1] neg_hi:[0,1]
	s_nop 0
	v_pk_mul_f32 v[14:15], v[14:15], v[16:17] op_sel:[1,0]
	s_nop 0
	v_pk_fma_f32 v[14:15], v[216:217], v[14:15], v[224:225]
	s_nop 0
	v_cvt_pk_bf16_f32 v13, v14, v15
	ds_write_b128 v160, v[10:13] offset:32768
	ds_write_b128 v162, v[2:5]
	ds_write_b128 v163, v[6:9]
	ds_write_b128 v164, v[30:33]
	ds_read_b64 v[6:7], v165
	v_lshlrev_b32_e32 v2, 16, v26
	v_and_b32_e32 v3, 0xffff0000, v26
	v_lshlrev_b32_e32 v4, 16, v27
	v_and_b32_e32 v5, 0xffff0000, v27
	s_waitcnt lgkmcnt(0)
; #define LAS __attribute__((address_space(3)))
; #define MFMA32(a, b, c) __builtin_amdgcn_mfma_f32_32x32x16_bf16((a), (b), (c), 0, 0, 0)
; __device__ __forceinline__ float bflo(unsigned w) { return __uint_as_float(w << 16); }
; __device__ __forceinline__ float bfhi(unsigned w) { return __uint_as_float(w & 0xffff0000u); }
; __device__ __forceinline__ unsigned pk2(float lo, float hi) { const f32x2v v = {lo, hi}; return __builtin_bit_cast(unsigned, __builtin_convertvector(v, bf16x2v)); }
; __device__ __forceinline__ void gmlp_item(LAS unsigned char* lds, const bf16_t* Zt  , bf16_t* BRt  , const bf16_t* wsb, const float* bs_, const float* lng, const float* lnb, const int tid) {
;     ...
;           for (int i = 0; i < 4; ++i) { const int t = t0 + 32 * i;
;               *(LAS u32x4*)(lds + off_b(t, ch)) = wb[i];
;               const float mean = st[2 * t], rstd = st[2 * t + 1];
;               u32x4 o;
;               o.x = pk2((bflo(vw[i].x) - mean) * rstd * g0[0] + b0[0], (bfhi(vw[i].x) - mean) * rstd * g0[1] + b0[1]);
;               o.y = pk2((bflo(vw[i].y) - mean) * rstd * g0[2] + b0[2], (bfhi(vw[i].y) - mean) * rstd * g0[3] + b0[3]);
;               o.z = pk2((bflo(vw[i].z) - mean) * rstd * g1[0] + b1[0], (bfhi(vw[i].z) - mean) * rstd * g1[1] + b1[1]);
;               o.w = pk2((bflo(vw[i].w) - mean) * rstd * g1[2] + b1[2], (bfhi(vw[i].w) - mean) * rstd * g1[3] + b1[3]);
;               *(LAS u32x4*)(lds + 32768 + off_b(t, ch)) = o;
;               *(LAS u32x4*)(lds + 65536 + off_b(t, ch)) = uu[i]; *(LAS u32x4*)(lds + 98304 + off_b(t, ch)) = gg4[i]; } }
;         __syncthreads();
;         f32x16 acc[2];
; #pragma unroll
;         for (int i = 0; i < 16; ++i) { acc[0][i] = 0.f; acc[1][i] = 0.f; }
; #pragma unroll
;         for (int ks = 0; ks < 8; ++ks) {
;             const bf16x8 af = *(LAS bf16x8*)(lds + aaddr[ks]);
; #pragma unroll
;             for (int cc = 0; cc < 2; ++cc) {
;                 const s16x4 lo = __builtin_amdgcn_ds_read_tr16_b64_v4i16((LAS s16x4*)(lds + baddr[cc][0] + ks * 4096));
;                 const s16x4 hi = __builtin_amdgcn_ds_read_tr16_b64_v4i16((LAS s16x4*)(lds + baddr[cc][1] + ks * 4096));
;                 const bf16x8 bfv = __builtin_shufflevector(lo, hi, 0, 1, 2, 3, 4, 5, 6, 7);
;                 acc[cc] = MFMA32(bfv, af, acc[cc]); }
	v_pk_add_f32 v[2:3], v[2:3], v[6:7] op_sel_hi:[1,0] neg_lo:[0,1] neg_hi:[0,1]
	v_pk_add_f32 v[4:5], v[4:5], v[6:7] op_sel_hi:[1,0] neg_lo:[0,1] neg_hi:[0,1]
	v_pk_mul_f32 v[2:3], v[6:7], v[2:3] op_sel:[1,0]
	v_pk_mul_f32 v[4:5], v[6:7], v[4:5] op_sel:[1,0]
	v_pk_fma_f32 v[2:3], v[218:219], v[2:3], v[232:233]
	v_pk_fma_f32 v[4:5], v[220:221], v[4:5], v[234:235]
	v_cvt_pk_bf16_f32 v2, v2, v3
	v_cvt_pk_bf16_f32 v3, v4, v5
	v_lshlrev_b32_e32 v4, 16, v28
	v_and_b32_e32 v5, 0xffff0000, v28
	v_lshlrev_b32_e32 v8, 16, v29
	v_and_b32_e32 v9, 0xffff0000, v29
	v_pk_add_f32 v[4:5], v[4:5], v[6:7] op_sel_hi:[1,0] neg_lo:[0,1] neg_hi:[0,1]
	v_pk_add_f32 v[8:9], v[8:9], v[6:7] op_sel_hi:[1,0] neg_lo:[0,1] neg_hi:[0,1]
	v_pk_mul_f32 v[4:5], v[6:7], v[4:5] op_sel:[1,0]
	v_pk_mul_f32 v[6:7], v[6:7], v[8:9] op_sel:[1,0]
	v_pk_fma_f32 v[4:5], v[214:215], v[4:5], v[222:223]
	v_pk_fma_f32 v[6:7], v[216:217], v[6:7], v[224:225]
	v_cvt_pk_bf16_f32 v4, v4, v5
	v_cvt_pk_bf16_f32 v5, v6, v7
	ds_write_b128 v164, v[2:5] offset:32768
	ds_write_b128 v166, v[18:21]
	ds_write_b128 v167, v[22:25]
	ds_write_b128 v168, v[46:49]
	ds_read_b64 v[6:7], v169
	v_lshlrev_b32_e32 v2, 16, v42
	v_and_b32_e32 v3, 0xffff0000, v42
	v_lshlrev_b32_e32 v4, 16, v43
	v_and_b32_e32 v5, 0xffff0000, v43
	s_waitcnt lgkmcnt(0)
	v_pk_add_f32 v[2:3], v[2:3], v[6:7] op_sel_hi:[1,0] neg_lo:[0,1] neg_hi:[0,1]
	v_pk_add_f32 v[4:5], v[4:5], v[6:7] op_sel_hi:[1,0] neg_lo:[0,1] neg_hi:[0,1]
	v_pk_mul_f32 v[2:3], v[6:7], v[2:3] op_sel:[1,0]
	v_pk_mul_f32 v[4:5], v[6:7], v[4:5] op_sel:[1,0]
	v_pk_fma_f32 v[2:3], v[218:219], v[2:3], v[232:233]
	v_pk_fma_f32 v[4:5], v[220:221], v[4:5], v[234:235]
	v_cvt_pk_bf16_f32 v2, v2, v3
	v_cvt_pk_bf16_f32 v3, v4, v5
	v_lshlrev_b32_e32 v4, 16, v44
	v_and_b32_e32 v5, 0xffff0000, v44
	v_lshlrev_b32_e32 v8, 16, v45
	v_and_b32_e32 v9, 0xffff0000, v45
	v_pk_add_f32 v[4:5], v[4:5], v[6:7] op_sel_hi:[1,0] neg_lo:[0,1] neg_hi:[0,1]
	v_pk_add_f32 v[8:9], v[8:9], v[6:7] op_sel_hi:[1,0] neg_lo:[0,1] neg_hi:[0,1]
	v_pk_mul_f32 v[4:5], v[6:7], v[4:5] op_sel:[1,0]
	v_pk_mul_f32 v[6:7], v[6:7], v[8:9] op_sel:[1,0]
	v_pk_fma_f32 v[4:5], v[214:215], v[4:5], v[222:223]
	v_pk_fma_f32 v[6:7], v[216:217], v[6:7], v[224:225]
	v_cvt_pk_bf16_f32 v4, v4, v5
	v_cvt_pk_bf16_f32 v5, v6, v7
	ds_write_b128 v168, v[2:5] offset:32768
	ds_write_b128 v170, v[34:37]
	ds_write_b128 v171, v[38:41]
	ds_write_b128 v172, v[62:65]
	ds_read_b64 v[6:7], v173
	v_lshlrev_b32_e32 v2, 16, v58
	v_and_b32_e32 v3, 0xffff0000, v58
	v_lshlrev_b32_e32 v4, 16, v59
	v_and_b32_e32 v5, 0xffff0000, v59
	s_waitcnt lgkmcnt(0)
	v_pk_add_f32 v[2:3], v[2:3], v[6:7] op_sel_hi:[1,0] neg_lo:[0,1] neg_hi:[0,1]
	v_pk_add_f32 v[4:5], v[4:5], v[6:7] op_sel_hi:[1,0] neg_lo:[0,1] neg_hi:[0,1]
	v_pk_mul_f32 v[2:3], v[6:7], v[2:3] op_sel:[1,0]
	v_pk_mul_f32 v[4:5], v[6:7], v[4:5] op_sel:[1,0]
	v_pk_fma_f32 v[2:3], v[218:219], v[2:3], v[232:233]
	v_pk_fma_f32 v[4:5], v[220:221], v[4:5], v[234:235]
	v_cvt_pk_bf16_f32 v2, v2, v3
	v_cvt_pk_bf16_f32 v3, v4, v5
	v_lshlrev_b32_e32 v4, 16, v60
	v_and_b32_e32 v5, 0xffff0000, v60
	v_lshlrev_b32_e32 v8, 16, v61
	v_and_b32_e32 v9, 0xffff0000, v61
	v_pk_add_f32 v[4:5], v[4:5], v[6:7] op_sel_hi:[1,0] neg_lo:[0,1] neg_hi:[0,1]
	v_pk_add_f32 v[8:9], v[8:9], v[6:7] op_sel_hi:[1,0] neg_lo:[0,1] neg_hi:[0,1]
	v_pk_mul_f32 v[4:5], v[6:7], v[4:5] op_sel:[1,0]
	v_pk_mul_f32 v[6:7], v[6:7], v[8:9] op_sel:[1,0]
	v_pk_fma_f32 v[4:5], v[214:215], v[4:5], v[222:223]
	v_pk_fma_f32 v[6:7], v[216:217], v[6:7], v[224:225]
	v_cvt_pk_bf16_f32 v4, v4, v5
	v_cvt_pk_bf16_f32 v5, v6, v7
	ds_write_b128 v172, v[2:5] offset:32768
	ds_write_b128 v179, v[50:53]
	ds_write_b128 v181, v[54:57]
	s_waitcnt lgkmcnt(0)
	s_barrier
	ds_read_b128 v[2:5], v184
	ds_read_b64_tr_b16 v[6:7], v185 offset:32768
	ds_read_b64_tr_b16 v[8:9], v186 offset:32768
	s_waitcnt lgkmcnt(0)
	v_mfma_f32_32x32x16_bf16 v[18:33], v[6:9], v[2:5], 0
	ds_read_b64_tr_b16 v[6:7], v187 offset:32768
	ds_read_b64_tr_b16 v[8:9], v188 offset:32768
	ds_read_b128 v[34:37], v189
	ds_read_b64_tr_b16 v[38:39], v185 offset:36864
	ds_read_b64_tr_b16 v[40:41], v186 offset:36864
	s_waitcnt lgkmcnt(3)
	v_mfma_f32_32x32x16_bf16 v[2:17], v[6:9], v[2:5], 0
	s_waitcnt lgkmcnt(0)
	v_mfma_f32_32x32x16_bf16 v[18:33], v[38:41], v[34:37], v[18:33]
	ds_read_b64_tr_b16 v[38:39], v187 offset:36864
	ds_read_b64_tr_b16 v[40:41], v188 offset:36864
	s_waitcnt lgkmcnt(0)
	v_mfma_f32_32x32x16_bf16 v[2:17], v[38:41], v[34:37], v[2:17]
	ds_read_b128 v[34:37], v190
	ds_read_b64_tr_b16 v[38:39], v185 offset:40960
	ds_read_b64_tr_b16 v[40:41], v186 offset:40960
	s_waitcnt lgkmcnt(0)
	v_mfma_f32_32x32x16_bf16 v[18:33], v[38:41], v[34:37], v[18:33]
	ds_read_b64_tr_b16 v[38:39], v187 offset:40960
	ds_read_b64_tr_b16 v[40:41], v188 offset:40960
	s_waitcnt lgkmcnt(0)
	v_mfma_f32_32x32x16_bf16 v[2:17], v[38:41], v[34:37], v[2:17]
	ds_read_b128 v[34:37], v191
	ds_read_b64_tr_b16 v[38:39], v185 offset:45056
	ds_read_b64_tr_b16 v[40:41], v186 offset:45056
	s_waitcnt lgkmcnt(0)
	v_mfma_f32_32x32x16_bf16 v[18:33], v[38:41], v[34:37], v[18:33]
	ds_read_b64_tr_b16 v[38:39], v187 offset:45056
	ds_read_b64_tr_b16 v[40:41], v188 offset:45056
	s_waitcnt lgkmcnt(0)
	v_mfma_f32_32x32x16_bf16 v[2:17], v[38:41], v[34:37], v[2:17]
	ds_read_b128 v[34:37], v192
	ds_read_b64_tr_b16 v[38:39], v185 offset:49152
	ds_read_b64_tr_b16 v[40:41], v186 offset:49152
	s_waitcnt lgkmcnt(0)
	v_mfma_f32_32x32x16_bf16 v[18:33], v[38:41], v[34:37], v[18:33]
	ds_read_b64_tr_b16 v[38:39], v187 offset:49152
	ds_read_b64_tr_b16 v[40:41], v188 offset:49152
	s_waitcnt lgkmcnt(0)
; #define LAS __attribute__((address_space(3)))
; #define MFMA32(a, b, c) __builtin_amdgcn_mfma_f32_32x32x16_bf16((a), (b), (c), 0, 0, 0)
; __device__ __forceinline__ float bflo(unsigned w) { return __uint_as_float(w << 16); }
; __device__ __forceinline__ float bfhi(unsigned w) { return __uint_as_float(w & 0xffff0000u); }
; __device__ __forceinline__ unsigned pk2(float lo, float hi) { const f32x2v v = {lo, hi}; return __builtin_bit_cast(unsigned, __builtin_convertvector(v, bf16x2v)); }
; __device__ __forceinline__ float silu_f(float g) { return g * fast_rcp(1.f + fast_exp2(-g * LOG2E)); }
; __device__ __forceinline__ void gmlp_item(LAS unsigned char* lds, const bf16_t* Zt  , bf16_t* BRt  , const bf16_t* wsb, const float* bs_, const float* lng, const float* lnb, const int tid) {
;     ...
;         for (int ks = 0; ks < 8; ++ks) {
;             const bf16x8 af = *(LAS bf16x8*)(lds + aaddr[ks]);
; #pragma unroll
;             for (int cc = 0; cc < 2; ++cc) {
;                 const s16x4 lo = __builtin_amdgcn_ds_read_tr16_b64_v4i16((LAS s16x4*)(lds + baddr[cc][0] + ks * 4096));
;                 const s16x4 hi = __builtin_amdgcn_ds_read_tr16_b64_v4i16((LAS s16x4*)(lds + baddr[cc][1] + ks * 4096));
;                 const bf16x8 bfv = __builtin_shufflevector(lo, hi, 0, 1, 2, 3, 4, 5, 6, 7);
;                 acc[cc] = MFMA32(bfv, af, acc[cc]); }
;         }
;         int r2 = r, h2 = h; asm volatile("" : "+v"(r2), "+v"(h2));
;         { const int t = 32 * tt + r2; const float bsv = bs_[g * 128 + t];
; #pragma unroll
;           for (int k8 = 0; k8 < 8; ++k8) { const int cc = k8 >> 2, q4 = k8 & 3;
;               const unsigned ad = off_b(t, 4 * (2 * cp + cc) + q4) + 8u * h2;
;               const u32x2 uw = *(const LAS u32x2*)(lds + 65536 + ad), gw = *(const LAS u32x2*)(lds + 98304 + ad);
;               const float v0 = bflo(uw.x) * (acc[cc][4 * q4 + 0] + bsv) * silu_f(bflo(gw.x)), v1 = bfhi(uw.x) * (acc[cc][4 * q4 + 1] + bsv) * silu_f(bfhi(gw.x));
;               const float v2 = bflo(uw.y) * (acc[cc][4 * q4 + 2] + bsv) * silu_f(bflo(gw.y)), v3 = bfhi(uw.y) * (acc[cc][4 * q4 + 3] + bsv) * silu_f(bfhi(gw.y));
;               u32x2 w; w.x = pk2(v0, v1); w.y = pk2(v2, v3);
;               *(LAS u32x2*)(lds + 65536 + ad) = w; } }
	v_mfma_f32_32x32x16_bf16 v[2:17], v[38:41], v[34:37], v[2:17]
	ds_read_b128 v[34:37], v193
	ds_read_b64_tr_b16 v[38:39], v185 offset:53248
	ds_read_b64_tr_b16 v[40:41], v186 offset:53248
	s_waitcnt lgkmcnt(0)
	v_mfma_f32_32x32x16_bf16 v[18:33], v[38:41], v[34:37], v[18:33]
	ds_read_b64_tr_b16 v[38:39], v187 offset:53248
	ds_read_b64_tr_b16 v[40:41], v188 offset:53248
	s_waitcnt lgkmcnt(0)
	v_mfma_f32_32x32x16_bf16 v[2:17], v[38:41], v[34:37], v[2:17]
	ds_read_b128 v[34:37], v194
	ds_read_b64_tr_b16 v[38:39], v185 offset:57344
	ds_read_b64_tr_b16 v[40:41], v186 offset:57344
	s_waitcnt lgkmcnt(0)
	v_mfma_f32_32x32x16_bf16 v[18:33], v[38:41], v[34:37], v[18:33]
	ds_read_b64_tr_b16 v[38:39], v187 offset:57344
	ds_read_b64_tr_b16 v[40:41], v188 offset:57344
	s_waitcnt lgkmcnt(0)
	v_mfma_f32_32x32x16_bf16 v[2:17], v[38:41], v[34:37], v[2:17]
	ds_read_b128 v[34:37], v195
	ds_read_b64_tr_b16 v[38:39], v185 offset:61440
	ds_read_b64_tr_b16 v[40:41], v186 offset:61440
	s_waitcnt lgkmcnt(0)
	v_mfma_f32_32x32x16_bf16 v[18:33], v[38:41], v[34:37], v[18:33]
	ds_read_b64_tr_b16 v[38:39], v187 offset:61440
	ds_read_b64_tr_b16 v[40:41], v188 offset:61440
	s_waitcnt lgkmcnt(0)
	v_mfma_f32_32x32x16_bf16 v[2:17], v[38:41], v[34:37], v[2:17]
	v_mov_b32_e32 v36, v75
	v_mov_b32_e32 v37, v132
	s_nop 0
	v_add_u32_e32 v34, s27, v36
	v_ashrrev_i32_e32 v35, 31, v34
	v_lshl_add_u64 v[34:35], v[34:35], 2, s[6:7]
	global_load_dword v34, v[34:35], off
	v_lshlrev_b32_e32 v35, 2, v36
	v_add_u32_e32 v38, s13, v36
	v_and_b32_e32 v35, 12, v35
	v_bfe_u32 v46, v36, 2, 2
	v_lshlrev_b32_e32 v36, 3, v37
	v_lshl_add_u32 v47, v38, 8, v36
	v_bitop3_b32 v36, v35, s12, v46 bitop3:0x36
	v_lshl_add_u32 v38, v36, 4, v47
	v_add_u32_e32 v48, s71, v38
	v_add_u32_e32 v38, s91, v38
	ds_read_b64 v[36:37], v48
	ds_read_b64 v[38:39], v38
	s_addk_i32 s27, 0x80
	s_cmpk_lg_i32 s10, 0x1600
	s_waitcnt lgkmcnt(1)
	v_lshlrev_b32_e32 v44, 16, v36
	s_waitcnt lgkmcnt(0)
	v_lshlrev_b32_e32 v40, 16, v38
	v_and_b32_e32 v41, 0xffff0000, v38
	v_mul_f32_e32 v38, 0xbfb8aa3b, v40
	v_and_b32_e32 v45, 0xffff0000, v36
	v_mul_f32_e32 v36, 0xbfb8aa3b, v41
	v_exp_f32_e32 v38, v38
	v_exp_f32_e32 v36, v36
	v_add_f32_e32 v38, 1.0, v38
	v_add_f32_e32 v36, 1.0, v36
	v_rcp_f32_e32 v42, v38
	v_rcp_f32_e32 v43, v36
	v_lshlrev_b32_e32 v38, 16, v39
	v_and_b32_e32 v39, 0xffff0000, v39
	v_mul_f32_e32 v36, 0xbfb8aa3b, v38
	v_pk_mul_f32 v[40:41], v[42:43], v[40:41]
	v_exp_f32_e32 v36, v36
	s_waitcnt vmcnt(0)
	v_pk_add_f32 v[18:19], v[18:19], v[34:35] op_sel_hi:[1,0]
	s_nop 0
	v_pk_mul_f32 v[18:19], v[18:19], v[44:45]
	v_add_f32_e32 v36, 1.0, v36
	v_pk_mul_f32 v[18:19], v[18:19], v[40:41]
	v_lshlrev_b32_e32 v40, 16, v37
	v_and_b32_e32 v41, 0xffff0000, v37
	v_mul_f32_e32 v37, 0xbfb8aa3b, v39
	v_exp_f32_e32 v37, v37
	v_rcp_f32_e32 v36, v36
	v_pk_add_f32 v[20:21], v[20:21], v[34:35] op_sel_hi:[1,0]
	v_cvt_pk_bf16_f32 v18, v18, v19
	v_add_f32_e32 v37, 1.0, v37
	v_rcp_f32_e32 v37, v37
	v_pk_mul_f32 v[20:21], v[20:21], v[40:41]
	v_pk_add_f32 v[22:23], v[22:23], v[34:35] op_sel_hi:[1,0]
	v_pk_add_f32 v[24:25], v[24:25], v[34:35] op_sel_hi:[1,0]
	v_pk_mul_f32 v[36:37], v[36:37], v[38:39]
	v_pk_add_f32 v[26:27], v[26:27], v[34:35] op_sel_hi:[1,0]
	v_pk_mul_f32 v[20:21], v[20:21], v[36:37]
	v_pk_add_f32 v[2:3], v[2:3], v[34:35] op_sel_hi:[1,0]
	v_cvt_pk_bf16_f32 v19, v20, v21
	ds_write_b64 v48, v[18:19]
	v_bitop3_b32 v18, v35, s14, v46 bitop3:0x36
	v_lshl_add_u32 v20, v18, 4, v47
	v_add_u32_e32 v42, s71, v20
	v_add_u32_e32 v20, s91, v20
	ds_read_b64 v[18:19], v42
	ds_read_b64 v[20:21], v20
	v_pk_add_f32 v[4:5], v[4:5], v[34:35] op_sel_hi:[1,0]
	v_pk_add_f32 v[6:7], v[6:7], v[34:35] op_sel_hi:[1,0]
	v_pk_add_f32 v[8:9], v[8:9], v[34:35] op_sel_hi:[1,0]
	s_waitcnt lgkmcnt(1)
	v_lshlrev_b32_e32 v40, 16, v18
	s_waitcnt lgkmcnt(0)
	v_lshlrev_b32_e32 v36, 16, v20
	v_and_b32_e32 v37, 0xffff0000, v20
	v_mul_f32_e32 v20, 0xbfb8aa3b, v36
	v_and_b32_e32 v41, 0xffff0000, v18
	v_mul_f32_e32 v18, 0xbfb8aa3b, v37
	v_exp_f32_e32 v20, v20
	v_exp_f32_e32 v18, v18
	v_pk_mul_f32 v[22:23], v[22:23], v[40:41]
	v_pk_add_f32 v[10:11], v[10:11], v[34:35] op_sel_hi:[1,0]
	v_add_f32_e32 v20, 1.0, v20
	v_add_f32_e32 v18, 1.0, v18
	v_rcp_f32_e32 v38, v20
	v_rcp_f32_e32 v39, v18
	v_lshlrev_b32_e32 v20, 16, v21
	v_and_b32_e32 v21, 0xffff0000, v21
	v_mul_f32_e32 v18, 0xbfb8aa3b, v20
	v_pk_mul_f32 v[36:37], v[38:39], v[36:37]
	v_exp_f32_e32 v18, v18
	v_pk_mul_f32 v[22:23], v[22:23], v[36:37]
	v_lshlrev_b32_e32 v36, 16, v19
	v_and_b32_e32 v37, 0xffff0000, v19
	v_mul_f32_e32 v19, 0xbfb8aa3b, v21
	v_exp_f32_e32 v19, v19
	v_add_f32_e32 v18, 1.0, v18
	v_rcp_f32_e32 v18, v18
	v_pk_mul_f32 v[24:25], v[24:25], v[36:37]
	v_add_f32_e32 v19, 1.0, v19
	v_rcp_f32_e32 v19, v19
	s_nop 0
	v_pk_mul_f32 v[18:19], v[18:19], v[20:21]
	s_nop 0
	v_pk_mul_f32 v[18:19], v[24:25], v[18:19]
	v_cvt_pk_bf16_f32 v20, v22, v23
	v_cvt_pk_bf16_f32 v21, v18, v19
	v_bitop3_b32 v18, v35, s15, v46 bitop3:0x36
	ds_write_b64 v42, v[20:21]
	v_lshl_add_u32 v20, v18, 4, v47
	v_add_u32_e32 v38, s71, v20
	v_add_u32_e32 v20, s91, v20
	ds_read_b64 v[18:19], v38
	ds_read_b64 v[20:21], v20
	s_waitcnt lgkmcnt(1)
	v_lshlrev_b32_e32 v36, 16, v18
	s_waitcnt lgkmcnt(0)
; #define LAS __attribute__((address_space(3)))
; __device__ __forceinline__ float bflo(unsigned w) { return __uint_as_float(w << 16); }
; __device__ __forceinline__ float bfhi(unsigned w) { return __uint_as_float(w & 0xffff0000u); }
; __device__ __forceinline__ unsigned pk2(float lo, float hi) { const f32x2v v = {lo, hi}; return __builtin_bit_cast(unsigned, __builtin_convertvector(v, bf16x2v)); }
; __device__ __forceinline__ float silu_f(float g) { return g * fast_rcp(1.f + fast_exp2(-g * LOG2E)); }
; __device__ __forceinline__ void gmlp_item(LAS unsigned char* lds, const bf16_t* Zt  , bf16_t* BRt  , const bf16_t* wsb, const float* bs_, const float* lng, const float* lnb, const int tid) {
;     ...
;           for (int k8 = 0; k8 < 8; ++k8) { const int cc = k8 >> 2, q4 = k8 & 3;
;               const unsigned ad = off_b(t, 4 * (2 * cp + cc) + q4) + 8u * h2;
;               const u32x2 uw = *(const LAS u32x2*)(lds + 65536 + ad), gw = *(const LAS u32x2*)(lds + 98304 + ad);
;               const float v0 = bflo(uw.x) * (acc[cc][4 * q4 + 0] + bsv) * silu_f(bflo(gw.x)), v1 = bfhi(uw.x) * (acc[cc][4 * q4 + 1] + bsv) * silu_f(bfhi(gw.x));
;               const float v2 = bflo(uw.y) * (acc[cc][4 * q4 + 2] + bsv) * silu_f(bflo(gw.y)), v3 = bfhi(uw.y) * (acc[cc][4 * q4 + 3] + bsv) * silu_f(bfhi(gw.y));
;               u32x2 w; w.x = pk2(v0, v1); w.y = pk2(v2, v3);
;               *(LAS u32x2*)(lds + 65536 + ad) = w; } }
	v_lshlrev_b32_e32 v22, 16, v20
	v_and_b32_e32 v23, 0xffff0000, v20
	v_mul_f32_e32 v20, 0xbfb8aa3b, v22
	v_and_b32_e32 v37, 0xffff0000, v18
	v_mul_f32_e32 v18, 0xbfb8aa3b, v23
	v_exp_f32_e32 v20, v20
	v_exp_f32_e32 v18, v18
	v_pk_mul_f32 v[26:27], v[26:27], v[36:37]
	v_add_f32_e32 v20, 1.0, v20
	v_add_f32_e32 v18, 1.0, v18
	v_rcp_f32_e32 v24, v20
	v_rcp_f32_e32 v25, v18
	v_lshlrev_b32_e32 v20, 16, v21
	v_and_b32_e32 v21, 0xffff0000, v21
	v_mul_f32_e32 v18, 0xbfb8aa3b, v20
	v_pk_mul_f32 v[22:23], v[24:25], v[22:23]
	v_lshlrev_b32_e32 v24, 16, v19
	v_and_b32_e32 v25, 0xffff0000, v19
	v_mul_f32_e32 v19, 0xbfb8aa3b, v21
	v_exp_f32_e32 v18, v18
	v_exp_f32_e32 v19, v19
	v_pk_mul_f32 v[22:23], v[26:27], v[22:23]
	v_pk_add_f32 v[26:27], v[28:29], v[34:35] op_sel_hi:[1,0]
	v_add_f32_e32 v18, 1.0, v18
	v_add_f32_e32 v19, 1.0, v19
	v_rcp_f32_e32 v18, v18
	v_rcp_f32_e32 v19, v19
	v_pk_mul_f32 v[24:25], v[26:27], v[24:25]
	v_pk_add_f32 v[28:29], v[30:31], v[34:35] op_sel_hi:[1,0]
	v_pk_mul_f32 v[18:19], v[18:19], v[20:21]
	s_nop 0
	v_pk_mul_f32 v[18:19], v[24:25], v[18:19]
	v_cvt_pk_bf16_f32 v20, v22, v23
	v_cvt_pk_bf16_f32 v21, v18, v19
	v_bitop3_b32 v18, v35, s16, v46 bitop3:0x36
	ds_write_b64 v38, v[20:21]
	v_lshl_add_u32 v20, v18, 4, v47
	v_add_u32_e32 v36, s71, v20
	v_add_u32_e32 v20, s91, v20
	ds_read_b64 v[18:19], v36
	ds_read_b64 v[20:21], v20
	s_waitcnt lgkmcnt(1)
	v_lshlrev_b32_e32 v26, 16, v18
	s_waitcnt lgkmcnt(0)
	v_lshlrev_b32_e32 v22, 16, v20
	v_and_b32_e32 v23, 0xffff0000, v20
	v_mul_f32_e32 v20, 0xbfb8aa3b, v22
	v_and_b32_e32 v27, 0xffff0000, v18
	v_mul_f32_e32 v18, 0xbfb8aa3b, v23
	v_exp_f32_e32 v20, v20
	v_exp_f32_e32 v18, v18
	v_pk_mul_f32 v[26:27], v[28:29], v[26:27]
	v_add_f32_e32 v20, 1.0, v20
	v_add_f32_e32 v18, 1.0, v18
	v_rcp_f32_e32 v24, v20
	v_rcp_f32_e32 v25, v18
	v_lshlrev_b32_e32 v20, 16, v21
	v_and_b32_e32 v21, 0xffff0000, v21
	v_mul_f32_e32 v18, 0xbfb8aa3b, v20
	v_pk_mul_f32 v[22:23], v[24:25], v[22:23]
	v_lshlrev_b32_e32 v24, 16, v19
	v_and_b32_e32 v25, 0xffff0000, v19
	v_mul_f32_e32 v19, 0xbfb8aa3b, v21
	v_exp_f32_e32 v18, v18
	v_exp_f32_e32 v19, v19
	v_pk_mul_f32 v[22:23], v[26:27], v[22:23]
	v_pk_add_f32 v[26:27], v[32:33], v[34:35] op_sel_hi:[1,0]
	v_add_f32_e32 v18, 1.0, v18
	v_add_f32_e32 v19, 1.0, v19
	v_rcp_f32_e32 v18, v18
	v_rcp_f32_e32 v19, v19
	v_pk_mul_f32 v[24:25], v[26:27], v[24:25]
	v_pk_mul_f32 v[18:19], v[18:19], v[20:21]
	s_nop 0
	v_pk_mul_f32 v[18:19], v[24:25], v[18:19]
	v_cvt_pk_bf16_f32 v20, v22, v23
	v_cvt_pk_bf16_f32 v21, v18, v19
	v_bitop3_b32 v18, v35, s17, v46 bitop3:0x36
	ds_write_b64 v36, v[20:21]
	v_lshl_add_u32 v20, v18, 4, v47
	v_add_u32_e32 v28, s71, v20
	v_add_u32_e32 v20, s91, v20
	ds_read_b64 v[18:19], v28
	ds_read_b64 v[20:21], v20
	s_waitcnt lgkmcnt(1)
	v_lshlrev_b32_e32 v26, 16, v18
	s_waitcnt lgkmcnt(0)
	v_lshlrev_b32_e32 v22, 16, v20
	v_and_b32_e32 v23, 0xffff0000, v20
	v_mul_f32_e32 v20, 0xbfb8aa3b, v22
	v_and_b32_e32 v27, 0xffff0000, v18
	v_mul_f32_e32 v18, 0xbfb8aa3b, v23
	v_exp_f32_e32 v20, v20
	v_exp_f32_e32 v18, v18
	v_pk_mul_f32 v[2:3], v[2:3], v[26:27]
	v_add_f32_e32 v20, 1.0, v20
	v_add_f32_e32 v18, 1.0, v18
	v_rcp_f32_e32 v24, v20
	v_rcp_f32_e32 v25, v18
	v_lshlrev_b32_e32 v20, 16, v21
	v_and_b32_e32 v21, 0xffff0000, v21
	v_mul_f32_e32 v18, 0xbfb8aa3b, v20
	v_pk_mul_f32 v[22:23], v[24:25], v[22:23]
	v_exp_f32_e32 v18, v18
	v_pk_mul_f32 v[2:3], v[2:3], v[22:23]
	v_lshlrev_b32_e32 v22, 16, v19
	v_and_b32_e32 v23, 0xffff0000, v19
	v_mul_f32_e32 v19, 0xbfb8aa3b, v21
	v_exp_f32_e32 v19, v19
	v_add_f32_e32 v18, 1.0, v18
	v_rcp_f32_e32 v18, v18
	v_pk_mul_f32 v[4:5], v[4:5], v[22:23]
	v_add_f32_e32 v19, 1.0, v19
	v_rcp_f32_e32 v19, v19
	v_cvt_pk_bf16_f32 v2, v2, v3
	v_pk_mul_f32 v[18:19], v[18:19], v[20:21]
	s_nop 0
	v_pk_mul_f32 v[4:5], v[4:5], v[18:19]
	s_nop 0
	v_cvt_pk_bf16_f32 v3, v4, v5
	ds_write_b64 v28, v[2:3]
	v_bitop3_b32 v2, v35, s18, v46 bitop3:0x36
	v_lshl_add_u32 v4, v2, 4, v47
	v_add_u32_e32 v24, s71, v4
	v_add_u32_e32 v4, s91, v4
	ds_read_b64 v[2:3], v24
	ds_read_b64 v[4:5], v4
	s_waitcnt lgkmcnt(1)
	v_lshlrev_b32_e32 v22, 16, v2
	s_waitcnt lgkmcnt(0)
; #define LAS __attribute__((address_space(3)))
; __device__ __forceinline__ float bflo(unsigned w) { return __uint_as_float(w << 16); }
; __device__ __forceinline__ float bfhi(unsigned w) { return __uint_as_float(w & 0xffff0000u); }
; __device__ __forceinline__ unsigned pk2(float lo, float hi) { const f32x2v v = {lo, hi}; return __builtin_bit_cast(unsigned, __builtin_convertvector(v, bf16x2v)); }
; __device__ __forceinline__ float silu_f(float g) { return g * fast_rcp(1.f + fast_exp2(-g * LOG2E)); }
; __device__ __forceinline__ void gmlp_item(LAS unsigned char* lds, const bf16_t* Zt  , bf16_t* BRt  , const bf16_t* wsb, const float* bs_, const float* lng, const float* lnb, const int tid) {
;     ...
;           for (int k8 = 0; k8 < 8; ++k8) { const int cc = k8 >> 2, q4 = k8 & 3;
;               const unsigned ad = off_b(t, 4 * (2 * cp + cc) + q4) + 8u * h2;
;               const u32x2 uw = *(const LAS u32x2*)(lds + 65536 + ad), gw = *(const LAS u32x2*)(lds + 98304 + ad);
;               const float v0 = bflo(uw.x) * (acc[cc][4 * q4 + 0] + bsv) * silu_f(bflo(gw.x)), v1 = bfhi(uw.x) * (acc[cc][4 * q4 + 1] + bsv) * silu_f(bfhi(gw.x));
;               const float v2 = bflo(uw.y) * (acc[cc][4 * q4 + 2] + bsv) * silu_f(bflo(gw.y)), v3 = bfhi(uw.y) * (acc[cc][4 * q4 + 3] + bsv) * silu_f(bfhi(gw.y));
;               u32x2 w; w.x = pk2(v0, v1); w.y = pk2(v2, v3);
;               *(LAS u32x2*)(lds + 65536 + ad) = w; } }
;         __syncthreads();
;     }
;     { const int ch = tid & 15, t0 = tid >> 4;
; #pragma unroll
;       for (int i = 0; i < 4; ++i) { const int t = t0 + 32 * i; const u32x4 ov = *(const LAS u32x4*)(lds + 65536 + off_b(t, ch)); *(u32x4*)(BRt + (size_t)t * DM + 11 * 128 + 8 * ch) = ov; } }
	v_lshlrev_b32_e32 v18, 16, v4
	v_and_b32_e32 v19, 0xffff0000, v4
	v_mul_f32_e32 v4, 0xbfb8aa3b, v18
	v_and_b32_e32 v23, 0xffff0000, v2
	v_mul_f32_e32 v2, 0xbfb8aa3b, v19
	v_exp_f32_e32 v4, v4
	v_exp_f32_e32 v2, v2
	v_pk_mul_f32 v[6:7], v[6:7], v[22:23]
	v_add_f32_e32 v4, 1.0, v4
	v_add_f32_e32 v2, 1.0, v2
	v_rcp_f32_e32 v20, v4
	v_rcp_f32_e32 v21, v2
	v_lshlrev_b32_e32 v4, 16, v5
	v_and_b32_e32 v5, 0xffff0000, v5
	v_mul_f32_e32 v2, 0xbfb8aa3b, v4
	v_pk_mul_f32 v[18:19], v[20:21], v[18:19]
	v_exp_f32_e32 v2, v2
	v_pk_mul_f32 v[6:7], v[6:7], v[18:19]
	v_lshlrev_b32_e32 v18, 16, v3
	v_and_b32_e32 v19, 0xffff0000, v3
	v_mul_f32_e32 v3, 0xbfb8aa3b, v5
	v_exp_f32_e32 v3, v3
	v_add_f32_e32 v2, 1.0, v2
	v_rcp_f32_e32 v2, v2
	v_pk_mul_f32 v[8:9], v[8:9], v[18:19]
	v_add_f32_e32 v3, 1.0, v3
	v_rcp_f32_e32 v3, v3
	s_nop 0
	v_pk_mul_f32 v[2:3], v[2:3], v[4:5]
	s_nop 0
	v_pk_mul_f32 v[2:3], v[8:9], v[2:3]
	v_cvt_pk_bf16_f32 v4, v6, v7
	v_cvt_pk_bf16_f32 v5, v2, v3
	v_bitop3_b32 v2, v35, s19, v46 bitop3:0x36
	ds_write_b64 v24, v[4:5]
	v_lshl_add_u32 v4, v2, 4, v47
	v_add_u32_e32 v20, s71, v4
	v_add_u32_e32 v4, s91, v4
	ds_read_b64 v[2:3], v20
	ds_read_b64 v[4:5], v4
	s_waitcnt lgkmcnt(1)
	v_lshlrev_b32_e32 v18, 16, v2
	s_waitcnt lgkmcnt(0)
	v_lshlrev_b32_e32 v6, 16, v4
	v_and_b32_e32 v7, 0xffff0000, v4
	v_mul_f32_e32 v4, 0xbfb8aa3b, v6
	v_and_b32_e32 v19, 0xffff0000, v2
	v_mul_f32_e32 v2, 0xbfb8aa3b, v7
	v_exp_f32_e32 v4, v4
	v_exp_f32_e32 v2, v2
	v_pk_mul_f32 v[10:11], v[10:11], v[18:19]
	v_add_f32_e32 v4, 1.0, v4
	v_add_f32_e32 v2, 1.0, v2
	v_rcp_f32_e32 v8, v4
	v_rcp_f32_e32 v9, v2
	v_lshlrev_b32_e32 v4, 16, v5
	v_and_b32_e32 v5, 0xffff0000, v5
	v_mul_f32_e32 v2, 0xbfb8aa3b, v4
	v_pk_mul_f32 v[6:7], v[8:9], v[6:7]
	v_lshlrev_b32_e32 v8, 16, v3
	v_and_b32_e32 v9, 0xffff0000, v3
	v_mul_f32_e32 v3, 0xbfb8aa3b, v5
	v_exp_f32_e32 v2, v2
	v_exp_f32_e32 v3, v3
	v_pk_mul_f32 v[6:7], v[10:11], v[6:7]
	v_pk_add_f32 v[10:11], v[12:13], v[34:35] op_sel_hi:[1,0]
	v_add_f32_e32 v2, 1.0, v2
	v_add_f32_e32 v3, 1.0, v3
	v_rcp_f32_e32 v2, v2
	v_rcp_f32_e32 v3, v3
	v_pk_mul_f32 v[8:9], v[10:11], v[8:9]
	v_pk_add_f32 v[12:13], v[14:15], v[34:35] op_sel_hi:[1,0]
	v_pk_mul_f32 v[2:3], v[2:3], v[4:5]
	s_nop 0
	v_pk_mul_f32 v[2:3], v[8:9], v[2:3]
	v_cvt_pk_bf16_f32 v4, v6, v7
	v_cvt_pk_bf16_f32 v5, v2, v3
	v_bitop3_b32 v2, v35, s26, v46 bitop3:0x36
	ds_write_b64 v20, v[4:5]
	v_lshl_add_u32 v4, v2, 4, v47
	v_add_u32_e32 v18, s71, v4
	v_add_u32_e32 v4, s91, v4
	ds_read_b64 v[2:3], v18
	ds_read_b64 v[4:5], v4
	s_waitcnt lgkmcnt(1)
	v_lshlrev_b32_e32 v10, 16, v2
	s_waitcnt lgkmcnt(0)
	v_lshlrev_b32_e32 v6, 16, v4
	v_and_b32_e32 v7, 0xffff0000, v4
	v_mul_f32_e32 v4, 0xbfb8aa3b, v6
	v_and_b32_e32 v11, 0xffff0000, v2
	v_mul_f32_e32 v2, 0xbfb8aa3b, v7
	v_exp_f32_e32 v4, v4
	v_exp_f32_e32 v2, v2
	v_pk_mul_f32 v[10:11], v[12:13], v[10:11]
	v_add_f32_e32 v4, 1.0, v4
	v_add_f32_e32 v2, 1.0, v2
	v_rcp_f32_e32 v8, v4
	v_rcp_f32_e32 v9, v2
	v_lshlrev_b32_e32 v4, 16, v5
	v_and_b32_e32 v5, 0xffff0000, v5
	v_mul_f32_e32 v2, 0xbfb8aa3b, v4
	v_pk_mul_f32 v[6:7], v[8:9], v[6:7]
	v_lshlrev_b32_e32 v8, 16, v3
	v_and_b32_e32 v9, 0xffff0000, v3
	v_mul_f32_e32 v3, 0xbfb8aa3b, v5
	v_exp_f32_e32 v2, v2
	v_exp_f32_e32 v3, v3
	v_pk_mul_f32 v[6:7], v[10:11], v[6:7]
	v_pk_add_f32 v[10:11], v[16:17], v[34:35] op_sel_hi:[1,0]
	v_add_f32_e32 v2, 1.0, v2
	v_add_f32_e32 v3, 1.0, v3
	v_rcp_f32_e32 v2, v2
	v_rcp_f32_e32 v3, v3
	v_pk_mul_f32 v[8:9], v[10:11], v[8:9]
	v_pk_mul_f32 v[2:3], v[2:3], v[4:5]
	s_nop 0
	v_pk_mul_f32 v[2:3], v[8:9], v[2:3]
	v_cvt_pk_bf16_f32 v4, v6, v7
	v_cvt_pk_bf16_f32 v5, v2, v3
	ds_write_b64 v18, v[4:5]
	s_waitcnt lgkmcnt(0)
	s_barrier
	s_cbranch_scc1 .LBB0_90
	s_lshl_b64 s[10:11], s[8:9], 19
	ds_read_b128 v[2:5], v196
	s_add_u32 s10, s93, s10
	s_addc_u32 s11, s95, s11
	v_lshl_add_u64 v[6:7], s[10:11], 0, v[98:99]
	v_lshl_add_u64 v[6:7], v[6:7], 0, v[0:1]
	s_waitcnt lgkmcnt(0)
	global_store_dwordx4 v[6:7], v[2:5], off offset:2816 sc1
	ds_read_b128 v[2:5], v197
	v_lshl_add_u64 v[6:7], s[10:11], 0, v[100:101]
	v_lshl_add_u64 v[6:7], v[6:7], 0, v[0:1]
	v_readlane_b32 s12, v252, 37
	v_readlane_b32 s13, v252, 38
	s_waitcnt lgkmcnt(0)
	global_store_dwordx4 v[6:7], v[2:5], off offset:2816 sc1
	ds_read_b128 v[2:5], v198
	v_lshl_add_u64 v[6:7], s[10:11], 0, v[102:103]
	v_lshl_add_u64 v[6:7], v[6:7], 0, v[0:1]
	s_add_i32 s8, s8, s64
	v_lshl_add_u64 v[106:107], v[106:107], 0, s[12:13]
	s_waitcnt lgkmcnt(0)
	global_store_dwordx4 v[6:7], v[2:5], off offset:2816 sc1
	ds_read_b128 v[2:5], v199
	v_lshl_add_u64 v[6:7], s[10:11], 0, v[104:105]
	v_readlane_b32 s10, v252, 58
	v_readlane_b32 s11, v252, 59
	v_lshl_add_u64 v[108:109], v[108:109], 0, s[12:13]
	s_cmpk_gt_i32 s8, 0xff
	v_lshl_add_u64 v[6:7], v[6:7], 0, v[0:1]
	v_lshl_add_u64 v[112:113], v[112:113], 0, s[10:11]
	s_waitcnt lgkmcnt(0)
	global_store_dwordx4 v[6:7], v[2:5], off offset:2816 sc1
	s_cbranch_scc0 .LBB0_79

; #define LAS __attribute__((address_space(3)))
; template <int MODE>
; __device__ __forceinline__ void attn_item(LAS unsigned char* lds, const AttnArgs& a, const int tid) {
;     ...
; #pragma unroll 4
;         for (int i = 0; i < 8; ++i) { const u32x4 ov = *(const LAS u32x4*)(lds + off_b(r0 + 32 * i, ch)); *(u32x4*)(a.O + (size_t)(a.q0 + r0 + 32 * i) * a.ldo + 8 * ch) = ov; }
.LBB0_101:
	ds_read_b128 v[6:9], v5
	v_add_u32_e32 v10, s4, v4
	v_ashrrev_i32_e32 v11, 31, v10
	v_lshlrev_b64 v[12:13], 12, v[10:11]
	v_lshl_add_u64 v[12:13], v[2:3], 0, v[12:13]
	s_waitcnt lgkmcnt(0)
	global_store_dwordx4 v[12:13], v[6:9], off offset:3072 sc1
	ds_read_b128 v[6:9], v5 offset:8192
	v_add_u32_e32 v12, 32, v10
	v_ashrrev_i32_e32 v13, 31, v12
	v_lshlrev_b64 v[12:13], 12, v[12:13]
	v_lshl_add_u64 v[12:13], v[2:3], 0, v[12:13]
	s_waitcnt lgkmcnt(0)
	global_store_dwordx4 v[12:13], v[6:9], off offset:3072 sc1
	ds_read_b128 v[6:9], v5 offset:16384
	v_add_u32_e32 v12, 64, v10
	v_ashrrev_i32_e32 v13, 31, v12
	v_lshlrev_b64 v[12:13], 12, v[12:13]
	v_lshl_add_u64 v[12:13], v[2:3], 0, v[12:13]
	s_waitcnt lgkmcnt(0)
	global_store_dwordx4 v[12:13], v[6:9], off offset:3072 sc1
	ds_read_b128 v[6:9], v5 offset:24576
	v_add_u32_e32 v10, 0x60, v10
	v_ashrrev_i32_e32 v11, 31, v10
	v_lshlrev_b64 v[10:11], 12, v[10:11]
	s_addk_i32 s4, 0x80
	v_lshl_add_u64 v[10:11], v[2:3], 0, v[10:11]
	v_add_u32_e32 v5, 0x8000, v5
	s_cmpk_lg_i32 s4, 0x100
	s_waitcnt lgkmcnt(0)
	global_store_dwordx4 v[10:11], v[6:9], off offset:3072 sc1
	s_cbranch_scc1 .LBB0_101
	s_add_i32 s18, s18, s64
	s_add_i32 s17, s17, s96
	s_cmpk_gt_i32 s18, 0x1ff
	s_cbranch_scc0 .LBB0_94
